# v23 + attention: the 32-term row sum moved from the tile tail into the shadow of the four PV MFMA groups (same order)
# speedup vs baseline: 1.0005x; 1.0005x over previous
.Latt_norescale:
	ds_read2_b64 v[68:71], v215 offset0:4 offset1:6
	ds_read2_b64 v[72:75], v214 offset0:36 offset1:38
	ds_read2_b64 v[76:79], v195 offset0:68 offset1:70
	ds_read2_b64 v[202:205], v193 offset0:100 offset1:102
	s_andn2_b64 vcc, exec, s[0:1]
	v_mfma_f32_32x32x16_bf16 v[48:63], v[172:175], v[64:67], v[48:63]
	v_mfma_f32_32x32x16_bf16 v[32:47], v[168:171], v[64:67], v[32:47]
	v_mfma_f32_32x32x16_bf16 v[16:31], v[164:167], v[64:67], v[16:31]
	v_mfma_f32_32x32x16_bf16 v[0:15], v[160:163], v[64:67], v[0:15]
	v_add_f32_e32 v231, 0, v82
	v_add_f32_e32 v231, v83, v231
	v_add_f32_e32 v231, v84, v231
	v_add_f32_e32 v231, v85, v231
	v_add_f32_e32 v231, v86, v231
	v_add_f32_e32 v231, v87, v231
	v_add_f32_e32 v231, v88, v231
	v_add_f32_e32 v231, v89, v231
	v_cvt_pk_bf16_f32 v64, v90, v91
	v_cvt_pk_bf16_f32 v65, v92, v93
	v_cvt_pk_bf16_f32 v66, v94, v95
	v_cvt_pk_bf16_f32 v67, v196, v197
	ds_read2_b64 v[160:163], v215 offset0:8 offset1:10
	ds_read2_b64 v[164:167], v214 offset0:40 offset1:42
	ds_read2_b64 v[168:171], v195 offset0:72 offset1:74
	ds_read2_b64 v[172:175], v193 offset0:104 offset1:106
	s_waitcnt lgkmcnt(4)
	s_nop 0
	v_mfma_f32_32x32x16_bf16 v[48:63], v[68:71], v[64:67], v[48:63]
	v_mfma_f32_32x32x16_bf16 v[32:47], v[72:75], v[64:67], v[32:47]
	v_mfma_f32_32x32x16_bf16 v[16:31], v[76:79], v[64:67], v[16:31]
	v_mfma_f32_32x32x16_bf16 v[0:15], v[202:205], v[64:67], v[0:15]
	v_add_f32_e32 v231, v90, v231
	v_add_f32_e32 v231, v91, v231
	v_add_f32_e32 v231, v92, v231
	v_add_f32_e32 v231, v93, v231
	v_add_f32_e32 v231, v94, v231
	v_add_f32_e32 v231, v95, v231
	v_add_f32_e32 v231, v196, v231
	v_add_f32_e32 v231, v197, v231
	v_cvt_pk_bf16_f32 v64, v216, v217
	v_cvt_pk_bf16_f32 v65, v218, v219
	v_cvt_pk_bf16_f32 v66, v220, v221
	v_cvt_pk_bf16_f32 v67, v242, v243
	ds_read2_b64 v[68:71], v215 offset0:12 offset1:14
	ds_read2_b64 v[72:75], v214 offset0:44 offset1:46
	ds_read2_b64 v[76:79], v195 offset0:76 offset1:78
	ds_read2_b64 v[202:205], v193 offset0:108 offset1:110
	s_waitcnt lgkmcnt(4)
	s_waitcnt lgkmcnt(0)
	v_mfma_f32_32x32x16_bf16 v[48:63], v[160:163], v[64:67], v[48:63]
	v_mfma_f32_32x32x16_bf16 v[32:47], v[164:167], v[64:67], v[32:47]
	v_mfma_f32_32x32x16_bf16 v[16:31], v[168:171], v[64:67], v[16:31]
	v_mfma_f32_32x32x16_bf16 v[0:15], v[172:175], v[64:67], v[0:15]
	v_add_f32_e32 v231, v216, v231
	v_add_f32_e32 v231, v217, v231
	v_add_f32_e32 v231, v218, v231
	v_add_f32_e32 v231, v219, v231
	v_add_f32_e32 v231, v220, v231
	v_add_f32_e32 v231, v221, v231
	v_add_f32_e32 v231, v242, v231
	v_add_f32_e32 v231, v243, v231
	v_cvt_pk_bf16_f32 v64, v244, v245
	v_cvt_pk_bf16_f32 v65, v246, v247
	v_cvt_pk_bf16_f32 v66, v248, v249
	v_cvt_pk_bf16_f32 v67, v250, v251
	s_nop 1
	v_mfma_f32_32x32x16_bf16 v[48:63], v[68:71], v[64:67], v[48:63]
	v_mfma_f32_32x32x16_bf16 v[32:47], v[72:75], v[64:67], v[32:47]
	v_mfma_f32_32x32x16_bf16 v[16:31], v[76:79], v[64:67], v[16:31]
	v_mfma_f32_32x32x16_bf16 v[0:15], v[202:205], v[64:67], v[0:15]
	v_add_f32_e32 v231, v244, v231
	v_add_f32_e32 v231, v245, v231
	v_add_f32_e32 v231, v246, v231
	v_add_f32_e32 v231, v247, v231
	v_add_f32_e32 v231, v248, v231
	v_add_f32_e32 v231, v249, v231
	v_add_f32_e32 v231, v250, v231
	v_add_f32_e32 v231, v251, v231
	s_cbranch_vccnz .LBB0_1555
	s_cmp_lt_u32 s6, 31
	s_cselect_b64 s[0:1], -1, 0
	s_and_b64 s[0:1], s[16:17], s[0:1]
	s_waitcnt vmcnt(4)
	v_mov_b64_e32 v[68:69], v[144:145]
	s_waitcnt vmcnt(3)
	v_mov_b64_e32 v[76:77], v[148:149]
	s_waitcnt vmcnt(1)
	v_mov_b64_e32 v[64:65], v[156:157]
	v_mov_b64_e32 v[72:73], v[152:153]
	s_andn2_b64 vcc, exec, s[0:1]
	v_mov_b64_e32 v[70:71], v[146:147]
	v_mov_b64_e32 v[78:79], v[150:151]
	v_mov_b64_e32 v[66:67], v[158:159]
	v_mov_b64_e32 v[74:75], v[154:155]
	s_cbranch_vccnz .LBB0_1554
	v_cvt_pk_bf16_f32 v68, v144, v145
	v_cvt_pk_bf16_f32 v69, v146, v147
	v_cvt_pk_bf16_f32 v70, v148, v149
	v_cvt_pk_bf16_f32 v71, v150, v151
	v_cvt_pk_bf16_f32 v76, v132, v133
	v_cvt_pk_bf16_f32 v77, v134, v135
	v_cvt_pk_bf16_f32 v78, v128, v129
	v_cvt_pk_bf16_f32 v79, v130, v131
	v_cvt_pk_bf16_f32 v64, v156, v157
	v_cvt_pk_bf16_f32 v65, v158, v159
	v_cvt_pk_bf16_f32 v66, v152, v153
	v_cvt_pk_bf16_f32 v67, v154, v155
	v_cvt_pk_bf16_f32 v72, v140, v141
	v_cvt_pk_bf16_f32 v73, v142, v143
	v_cvt_pk_bf16_f32 v74, v136, v137
	v_cvt_pk_bf16_f32 v75, v138, v139

; __device__ __forceinline__ void attn_unit(const Frame& F, int l, int samp, int b, int c, int g) {
;     ...
;     for (int t = 0; t < ntiles; ++t) {
;         const int buf = t & 1;
;         if (t + 1 < ntiles) ATT_LOAD(t + 1);
;         ATT_COMPUTE(buf, mwc);
;         if (t + 1 < ntiles) ATT_WRITE(buf ^ 1, t + 1);
;         mwc = mwn; asm volatile("" : "+v"(mwc));
;         __syncthreads();
.LBB0_1555:
	v_mov_b32_e32 v64, v231
	v_fmac_f32_e32 v64, v213, v80
	s_waitcnt vmcnt(0)
	v_mov_b64_e32 v[196:197], v[180:181]
	v_lshl_add_u64 v[188:189], v[188:189], 0, 8
	v_lshl_add_u64 v[190:191], v[190:191], 0, s[72:73]
	v_add_u32_e32 v192, 64, v192
	v_add_u32_e32 v194, 64, v194
	s_cmp_lg_u32 s22, s7
	v_add_u32_e32 v200, 0x4000, v200
	s_waitcnt lgkmcnt(0)
	s_barrier
	s_cbranch_scc0 .LBB0_1557
	v_mov_b32_e32 v216, v81
	v_mov_b32_e32 v213, v64
	s_mov_b32 s6, s7
	s_branch .LBB0_1545

.Latt2_norescale:
	ds_read2_b64 v[68:71], v215 offset0:4 offset1:6
	ds_read2_b64 v[72:75], v214 offset0:36 offset1:38
	ds_read2_b64 v[76:79], v195 offset0:68 offset1:70
	ds_read2_b64 v[202:205], v193 offset0:100 offset1:102
	s_andn2_b64 vcc, exec, s[0:1]
	v_mfma_f32_32x32x16_bf16 v[48:63], v[172:175], v[64:67], v[48:63]
	v_mfma_f32_32x32x16_bf16 v[32:47], v[168:171], v[64:67], v[32:47]
	v_mfma_f32_32x32x16_bf16 v[16:31], v[164:167], v[64:67], v[16:31]
	v_mfma_f32_32x32x16_bf16 v[0:15], v[160:163], v[64:67], v[0:15]
	v_add_f32_e32 v231, 0, v82
	v_add_f32_e32 v231, v83, v231
	v_add_f32_e32 v231, v84, v231
	v_add_f32_e32 v231, v85, v231
	v_add_f32_e32 v231, v86, v231
	v_add_f32_e32 v231, v87, v231
	v_add_f32_e32 v231, v88, v231
	v_add_f32_e32 v231, v89, v231
	v_cvt_pk_bf16_f32 v64, v90, v91
	v_cvt_pk_bf16_f32 v65, v92, v93
	v_cvt_pk_bf16_f32 v66, v94, v95
	v_cvt_pk_bf16_f32 v67, v196, v197
	ds_read2_b64 v[160:163], v215 offset0:8 offset1:10
	ds_read2_b64 v[164:167], v214 offset0:40 offset1:42
	ds_read2_b64 v[168:171], v195 offset0:72 offset1:74
	ds_read2_b64 v[172:175], v193 offset0:104 offset1:106
	s_waitcnt lgkmcnt(4)
	s_nop 0
	v_mfma_f32_32x32x16_bf16 v[48:63], v[68:71], v[64:67], v[48:63]
	v_mfma_f32_32x32x16_bf16 v[32:47], v[72:75], v[64:67], v[32:47]
	v_mfma_f32_32x32x16_bf16 v[16:31], v[76:79], v[64:67], v[16:31]
	v_mfma_f32_32x32x16_bf16 v[0:15], v[202:205], v[64:67], v[0:15]
	v_add_f32_e32 v231, v90, v231
	v_add_f32_e32 v231, v91, v231
	v_add_f32_e32 v231, v92, v231
	v_add_f32_e32 v231, v93, v231
	v_add_f32_e32 v231, v94, v231
	v_add_f32_e32 v231, v95, v231
	v_add_f32_e32 v231, v196, v231
	v_add_f32_e32 v231, v197, v231
	v_cvt_pk_bf16_f32 v64, v216, v217
	v_cvt_pk_bf16_f32 v65, v218, v219
	v_cvt_pk_bf16_f32 v66, v220, v221
	v_cvt_pk_bf16_f32 v67, v242, v243
	ds_read2_b64 v[68:71], v215 offset0:12 offset1:14
	ds_read2_b64 v[72:75], v214 offset0:44 offset1:46
	ds_read2_b64 v[76:79], v195 offset0:76 offset1:78
	ds_read2_b64 v[202:205], v193 offset0:108 offset1:110
	s_waitcnt lgkmcnt(4)
	s_waitcnt lgkmcnt(0)
	v_mfma_f32_32x32x16_bf16 v[48:63], v[160:163], v[64:67], v[48:63]
	v_mfma_f32_32x32x16_bf16 v[32:47], v[164:167], v[64:67], v[32:47]
	v_mfma_f32_32x32x16_bf16 v[16:31], v[168:171], v[64:67], v[16:31]
	v_mfma_f32_32x32x16_bf16 v[0:15], v[172:175], v[64:67], v[0:15]
	v_add_f32_e32 v231, v216, v231
	v_add_f32_e32 v231, v217, v231
	v_add_f32_e32 v231, v218, v231
	v_add_f32_e32 v231, v219, v231
	v_add_f32_e32 v231, v220, v231
	v_add_f32_e32 v231, v221, v231
	v_add_f32_e32 v231, v242, v231
	v_add_f32_e32 v231, v243, v231
	v_cvt_pk_bf16_f32 v64, v244, v245
	v_cvt_pk_bf16_f32 v65, v246, v247
	v_cvt_pk_bf16_f32 v66, v248, v249
	v_cvt_pk_bf16_f32 v67, v250, v251
	s_nop 1
	v_mfma_f32_32x32x16_bf16 v[48:63], v[68:71], v[64:67], v[48:63]
	v_mfma_f32_32x32x16_bf16 v[32:47], v[72:75], v[64:67], v[32:47]
	v_mfma_f32_32x32x16_bf16 v[16:31], v[76:79], v[64:67], v[16:31]
	v_mfma_f32_32x32x16_bf16 v[0:15], v[202:205], v[64:67], v[0:15]
	v_add_f32_e32 v231, v244, v231
	v_add_f32_e32 v231, v245, v231
	v_add_f32_e32 v231, v246, v231
	v_add_f32_e32 v231, v247, v231
	v_add_f32_e32 v231, v248, v231
	v_add_f32_e32 v231, v249, v231
	v_add_f32_e32 v231, v250, v231
	v_add_f32_e32 v231, v251, v231
	s_cbranch_vccnz .Lad_1555
	s_add_i32 s0, s6, 2
	s_cmp_lt_u32 s0, s22
	s_cbranch_scc1 .Lad_w5
	s_waitcnt vmcnt(0)
	s_branch .Lad_w

; __device__ __forceinline__ void attn_unit(const Frame& F, int l, int samp, int b, int c, int g) {
;     ...
;     ATT_LOAD(0);
;     ATT_WRITE(0, 0); mwc = mwn;
;     __syncthreads();
;     for (int t = 0; t < ntiles; ++t) {
;         const int buf = t & 1;
;         if (t + 1 < ntiles) ATT_LOAD(t + 1);
;         ATT_COMPUTE(buf, mwc);
;         if (t + 1 < ntiles) ATT_WRITE(buf ^ 1, t + 1);
;         mwc = mwn; asm volatile("" : "+v"(mwc));
.Lad_1555:
	v_mov_b32_e32 v64, v231
	v_fmac_f32_e32 v64, v213, v80
	s_bitcmp1_b32 s6, 0
	s_cbranch_scc1 .Lad_mB
	v_mov_b64_e32 v[196:197], v[180:181]
	s_branch .Lad_m
